# P1 adaLN weight stream as dwordx4 loads interleaved into MFMA section; S5 emit-loop store wait relaxed
# speedup vs baseline: 1.0013x; 1.0013x over previous
.LBB0_107:
	s_and_b32 s29, s28, 1
	s_bfe_i32 s12, s28, 0x10000
	s_lshr_b32 s8, s28, 1
	s_cmp_eq_u32 s29, 0
	s_cselect_b64 s[14:15], -1, 0
	s_cmp_eq_u32 s29, 1
	s_mul_i32 s13, s8, 0x90
	s_cselect_b64 s[8:9], -1, 0
	s_and_b32 s12, s12, 0x50
	s_add_i32 s12, s12, s13
	s_ashr_i32 s13, s12, 31
	v_lshl_add_u64 v[94:95], s[12:13], 2, v[80:81]
	s_load_dwordx2 s[100:101], s[0:1], 0x38
	v_lshrrev_b32_e32 v204, 4, v162
	v_mul_u32_u24_e32 v204, 0x90000, v204
	v_and_b32_e32 v205, 15, v162
	s_lshl_b32 s98, s12, 2
	v_lshl_add_u32 v206, v205, 2, s98
	v_lshl_add_u32 v207, v205, 4, s98
	v_add_u32_e32 v205, v204, v206
	v_add_u32_e32 v204, v204, v207
	v_and_b32_e32 v206, 15, v162
	v_lshrrev_b32_e32 v207, 2, v206
	v_and_b32_e32 v206, 3, v206
	v_lshlrev_b32_e32 v206, 6, v206
	v_lshl_add_u32 v206, v207, 10, v206
	v_lshrrev_b32_e32 v207, 4, v162
	v_lshl_add_u32 v206, v207, 8, v206
	v_add_u32_e32 v206, s21, v206
	s_mul_i32 s98, s91, 0x240000
	s_waitcnt lgkmcnt(0)
	s_add_u32 s100, s100, s98
	s_addc_u32 s101, s101, 0
	v_cndmask_b32_e64 v3, 0, 1, s[14:15]
	s_mov_b32 s98, s100
	s_mov_b32 s99, s101
	v_cmp_ne_u32_e64 s[8:9], 1, v3
	s_nop 1
	global_load_dwordx4 v[164:167], v204, s[98:99] nt
	s_add_u32 s98, s98, 0x12000
	s_addc_u32 s99, s99, 0
	global_load_dwordx4 v[168:171], v204, s[98:99] nt
	s_add_u32 s98, s98, 0x12000
	s_addc_u32 s99, s99, 0
	global_load_dwordx4 v[172:175], v204, s[98:99] nt
	s_add_u32 s98, s98, 0x12000
	s_addc_u32 s99, s99, 0
	global_load_dwordx4 v[176:179], v204, s[98:99] nt
	s_add_u32 s98, s98, 0x12000
	s_addc_u32 s99, s99, 0
	global_load_dwordx4 v[180:183], v204, s[98:99] nt
	s_add_u32 s98, s98, 0x12000
	s_addc_u32 s99, s99, 0
	global_load_dwordx4 v[184:187], v204, s[98:99] nt
	s_add_u32 s98, s98, 0x12000
	s_addc_u32 s99, s99, 0
	global_load_dwordx4 v[188:191], v204, s[98:99] nt
	s_add_u32 s98, s98, 0x12000
	s_addc_u32 s99, s99, 0
	global_load_dwordx4 v[192:195], v204, s[98:99] nt
	s_and_b64 vcc, exec, s[8:9]
	s_cbranch_vccnz .Lp1_skipE_h
	s_sub_u32 s98, s98, 0x7e000
	s_subb_u32 s99, s99, 0
	global_load_dword v196, v205, s[98:99] offset:256 nt
	s_add_u32 s98, s98, 0x12000
	s_addc_u32 s99, s99, 0
	global_load_dword v197, v205, s[98:99] offset:256 nt
	s_add_u32 s98, s98, 0x12000
	s_addc_u32 s99, s99, 0
	global_load_dword v198, v205, s[98:99] offset:256 nt
	s_add_u32 s98, s98, 0x12000
	s_addc_u32 s99, s99, 0
	global_load_dword v199, v205, s[98:99] offset:256 nt
	s_add_u32 s98, s98, 0x12000
	s_addc_u32 s99, s99, 0
	global_load_dword v200, v205, s[98:99] offset:256 nt
	s_add_u32 s98, s98, 0x12000
	s_addc_u32 s99, s99, 0
	global_load_dword v201, v205, s[98:99] offset:256 nt
	s_add_u32 s98, s98, 0x12000
	s_addc_u32 s99, s99, 0
	global_load_dword v202, v205, s[98:99] offset:256 nt
	s_add_u32 s98, s98, 0x12000
	s_addc_u32 s99, s99, 0
	global_load_dword v203, v205, s[98:99] offset:256 nt
.Lp1_skipE_h:
.LBB0_123:
	v_mov_b32_e32 v4, v2
	v_mov_b32_e32 v5, v2
	v_mov_b32_e32 v3, v2
	v_mov_b64_e32 v[10:11], v[4:5]
	v_mov_b32_e32 v28, 0
	v_mov_b64_e32 v[8:9], v[2:3]
	v_mov_b64_e32 v[6:7], v[4:5]
	s_mov_b32 s13, 0
	s_mov_b64 s[16:17], 0
	s_mov_b32 s18, s3
	v_mov_b64_e32 v[4:5], v[2:3]
	v_mov_b32_e32 v29, v28
	v_mov_b32_e32 v30, v28
	v_mov_b32_e32 v31, v28
	v_mov_b32_e32 v32, v28
	v_mov_b32_e32 v33, v28
	v_mov_b32_e32 v34, v28
	v_mov_b32_e32 v35, v28
	v_mov_b32_e32 v36, v28
	v_mov_b32_e32 v37, v28
	v_mov_b32_e32 v38, v28
	v_mov_b32_e32 v39, v28
	v_mov_b32_e32 v40, v28
	v_mov_b32_e32 v41, v28
	v_mov_b32_e32 v42, v28
	v_mov_b32_e32 v43, v28
	v_mov_b32_e32 v12, v28
	v_mov_b32_e32 v13, v28
	v_mov_b32_e32 v14, v28
	v_mov_b32_e32 v15, v28
	v_mov_b32_e32 v16, v28
	v_mov_b32_e32 v17, v28
	v_mov_b32_e32 v18, v28
	v_mov_b32_e32 v19, v28
	v_mov_b32_e32 v20, v28
	v_mov_b32_e32 v21, v28
	v_mov_b32_e32 v22, v28
	v_mov_b32_e32 v23, v28
	v_mov_b32_e32 v24, v28
	v_mov_b32_e32 v25, v28
	v_mov_b32_e32 v26, v28
	v_mov_b32_e32 v27, v28
.LBB0_124:
	s_bitcmp1_b32 s13, 0
	s_cselect_b32 s19, 0xa000, 0
	v_add_u32_e32 v141, s19, v98
	v_add_u32_e32 v3, s21, v141
	v_add_u32_e32 v207, s19, v206
	s_waitcnt vmcnt(0)
	v_cvt_pk_bf16_f32 v44, v164, v168
	v_cvt_pk_bf16_f32 v45, v172, v176
	v_cvt_pk_bf16_f32 v46, v180, v184
	v_cvt_pk_bf16_f32 v47, v188, v192
	ds_write_b128 v207, v[44:47]
	v_cvt_pk_bf16_f32 v44, v165, v169
	v_cvt_pk_bf16_f32 v45, v173, v177
	v_cvt_pk_bf16_f32 v46, v181, v185
	v_cvt_pk_bf16_f32 v47, v189, v193
	ds_write_b128 v207, v[44:47] offset:16
	v_cvt_pk_bf16_f32 v44, v166, v170
	v_cvt_pk_bf16_f32 v45, v174, v178
	v_cvt_pk_bf16_f32 v46, v182, v186
	v_cvt_pk_bf16_f32 v47, v190, v194
	ds_write_b128 v207, v[44:47] offset:32
	v_cvt_pk_bf16_f32 v44, v167, v171
	v_cvt_pk_bf16_f32 v45, v175, v179
	v_cvt_pk_bf16_f32 v46, v183, v187
	v_cvt_pk_bf16_f32 v47, v191, v195
	ds_write_b128 v207, v[44:47] offset:48
	s_and_b64 vcc, exec, s[8:9]
	s_cbranch_vccnz .LBB0_126
	v_cvt_pk_bf16_f32 v44, v196, v197
	v_cvt_pk_bf16_f32 v45, v198, v199
	v_cvt_pk_bf16_f32 v46, v200, v201
	v_cvt_pk_bf16_f32 v47, v202, v203
	ds_write_b128 v3, v[44:47] offset:4096
.LBB0_126:
	v_lshl_add_u64 v[44:45], v[92:93], 0, s[16:17]
	v_add_co_u32_e32 v48, vcc, 0xdd00000, v44
	s_ashr_i32 s19, s18, 31
	s_nop 0
	v_addc_co_u32_e32 v49, vcc, 0, v45, vcc
	global_load_dwordx4 v[76:79], v[48:49], off
	v_lshl_add_u64 v[50:51], s[18:19], 1, v[84:85]
	global_load_dwordx4 v[44:47], v[50:51], off
	global_load_dwordx4 v[72:75], v[48:49], off offset:64
	global_load_dwordx4 v[68:71], v[48:49], off offset:128
	global_load_dwordx4 v[64:67], v[48:49], off offset:192
	global_load_dwordx4 v[60:63], v[48:49], off offset:256
	global_load_dwordx4 v[56:59], v[48:49], off offset:320
	global_load_dwordx4 v[52:55], v[48:49], off offset:384
	s_nop 0
	global_load_dwordx4 v[48:51], v[48:49], off offset:448
	s_add_i32 s24, s18, 0x100
	s_add_i32 s98, s13, 1
	s_mul_i32 s98, s98, 0x1200000
	s_add_u32 s98, s100, s98
	s_addc_u32 s99, s101, 0
.LBB0_142:
	s_waitcnt lgkmcnt(0)
	s_waitcnt lgkmcnt(0)
	s_barrier
	ds_read_b128 v[142:145], v141
	ds_read_b128 v[146:149], v141 offset:1024
	s_and_b64 vcc, exec, s[8:9]
	s_waitcnt vmcnt(8) lgkmcnt(1)
	v_mfma_f32_16x16x32_bf16 v[40:43], v[142:145], v[76:79], v[40:43]
	ds_read_b128 v[142:145], v141 offset:2048
	s_waitcnt lgkmcnt(1)
	v_mfma_f32_16x16x32_bf16 v[36:39], v[146:149], v[76:79], v[36:39]
	ds_read_b128 v[146:149], v141 offset:3072
	s_waitcnt lgkmcnt(1)
	v_mfma_f32_16x16x32_bf16 v[32:35], v[142:145], v[76:79], v[32:35]
	s_waitcnt lgkmcnt(0)
	v_mfma_f32_16x16x32_bf16 v[28:31], v[146:149], v[76:79], v[28:31]
	s_cbranch_vccnz .LBB0_144
	ds_read_b128 v[142:145], v141 offset:4096
	s_waitcnt lgkmcnt(0)
	v_mfma_f32_16x16x32_bf16 v[8:11], v[142:145], v[76:79], v[8:11]
.LBB0_144:
	global_load_dwordx4 v[164:167], v204, s[98:99] nt
	s_and_b64 vcc, exec, s[8:9]
	s_cbranch_vccnz .Lp1_skipE_l0
	global_load_dword v196, v205, s[98:99] offset:256 nt
.Lp1_skipE_l0:
	s_add_u32 s98, s98, 0x12000
	s_addc_u32 s99, s99, 0
	global_load_dwordx4 v[168:171], v204, s[98:99] nt
	s_and_b64 vcc, exec, s[8:9]
	s_cbranch_vccnz .Lp1_skipE_l1
	global_load_dword v197, v205, s[98:99] offset:256 nt
.Lp1_skipE_l1:
	s_add_u32 s98, s98, 0x12000
	s_addc_u32 s99, s99, 0
	ds_read_b128 v[76:79], v141 offset:5120
	ds_read_b128 v[142:145], v141 offset:6144
	s_and_b64 vcc, exec, s[8:9]
	s_waitcnt vmcnt(8) lgkmcnt(1)
	v_mfma_f32_16x16x32_bf16 v[40:43], v[76:79], v[72:75], v[40:43]
	ds_read_b128 v[76:79], v141 offset:7168
	s_waitcnt lgkmcnt(1)
	v_mfma_f32_16x16x32_bf16 v[36:39], v[142:145], v[72:75], v[36:39]
	ds_read_b128 v[142:145], v141 offset:8192
	s_waitcnt lgkmcnt(1)
	v_mfma_f32_16x16x32_bf16 v[32:35], v[76:79], v[72:75], v[32:35]
	s_waitcnt lgkmcnt(0)
	v_mfma_f32_16x16x32_bf16 v[28:31], v[142:145], v[72:75], v[28:31]
	s_cbranch_vccnz .LBB0_146
	ds_read_b128 v[76:79], v141 offset:9216
	s_waitcnt lgkmcnt(0)
	v_mfma_f32_16x16x32_bf16 v[8:11], v[76:79], v[72:75], v[8:11]
.LBB0_146:
	global_load_dwordx4 v[172:175], v204, s[98:99] nt
	s_and_b64 vcc, exec, s[8:9]
	s_cbranch_vccnz .Lp1_skipE_l2
	global_load_dword v198, v205, s[98:99] offset:256 nt
.Lp1_skipE_l2:
	s_add_u32 s98, s98, 0x12000
	s_addc_u32 s99, s99, 0
	global_load_dwordx4 v[176:179], v204, s[98:99] nt
	s_and_b64 vcc, exec, s[8:9]
	s_cbranch_vccnz .Lp1_skipE_l3
	global_load_dword v199, v205, s[98:99] offset:256 nt
.Lp1_skipE_l3:
	s_add_u32 s98, s98, 0x12000
	s_addc_u32 s99, s99, 0
	ds_read_b128 v[72:75], v141 offset:10240
	ds_read_b128 v[76:79], v141 offset:11264
	s_and_b64 vcc, exec, s[8:9]
	s_waitcnt vmcnt(9) lgkmcnt(1)
	v_mfma_f32_16x16x32_bf16 v[40:43], v[72:75], v[68:71], v[40:43]
	ds_read_b128 v[72:75], v141 offset:12288
	s_waitcnt lgkmcnt(1)
	v_mfma_f32_16x16x32_bf16 v[36:39], v[76:79], v[68:71], v[36:39]
	ds_read_b128 v[76:79], v141 offset:13312
	s_waitcnt lgkmcnt(1)
	v_mfma_f32_16x16x32_bf16 v[32:35], v[72:75], v[68:71], v[32:35]
	s_waitcnt lgkmcnt(0)
	v_mfma_f32_16x16x32_bf16 v[28:31], v[76:79], v[68:71], v[28:31]
	s_cbranch_vccnz .LBB0_148
	ds_read_b128 v[72:75], v141 offset:14336
	s_waitcnt lgkmcnt(0)
	v_mfma_f32_16x16x32_bf16 v[8:11], v[72:75], v[68:71], v[8:11]
.LBB0_148:
	global_load_dwordx4 v[180:183], v204, s[98:99] nt
	s_and_b64 vcc, exec, s[8:9]
	s_cbranch_vccnz .Lp1_skipE_l4
	global_load_dword v200, v205, s[98:99] offset:256 nt
.Lp1_skipE_l4:
	s_add_u32 s98, s98, 0x12000
	s_addc_u32 s99, s99, 0
	global_load_dwordx4 v[184:187], v204, s[98:99] nt
	s_and_b64 vcc, exec, s[8:9]
	s_cbranch_vccnz .Lp1_skipE_l5
	global_load_dword v201, v205, s[98:99] offset:256 nt
.Lp1_skipE_l5:
	s_add_u32 s98, s98, 0x12000
	s_addc_u32 s99, s99, 0
	ds_read_b128 v[68:71], v141 offset:15360
	ds_read_b128 v[72:75], v141 offset:16384
	s_and_b64 vcc, exec, s[8:9]
	s_waitcnt vmcnt(10) lgkmcnt(1)
	v_mfma_f32_16x16x32_bf16 v[40:43], v[68:71], v[64:67], v[40:43]
	ds_read_b128 v[68:71], v141 offset:17408
	s_waitcnt lgkmcnt(1)
	v_mfma_f32_16x16x32_bf16 v[36:39], v[72:75], v[64:67], v[36:39]
	ds_read_b128 v[72:75], v141 offset:18432
	s_waitcnt lgkmcnt(1)
	v_mfma_f32_16x16x32_bf16 v[32:35], v[68:71], v[64:67], v[32:35]
	s_waitcnt lgkmcnt(0)
	v_mfma_f32_16x16x32_bf16 v[28:31], v[72:75], v[64:67], v[28:31]
	s_cbranch_vccnz .LBB0_150
	ds_read_b128 v[68:71], v141 offset:19456
	s_waitcnt lgkmcnt(0)
	v_mfma_f32_16x16x32_bf16 v[8:11], v[68:71], v[64:67], v[8:11]
.LBB0_150:
	global_load_dwordx4 v[188:191], v204, s[98:99] nt
	s_and_b64 vcc, exec, s[8:9]
	s_cbranch_vccnz .Lp1_skipE_l6
	global_load_dword v202, v205, s[98:99] offset:256 nt
.Lp1_skipE_l6:
	s_add_u32 s98, s98, 0x12000
	s_addc_u32 s99, s99, 0
	global_load_dwordx4 v[192:195], v204, s[98:99] nt
	s_and_b64 vcc, exec, s[8:9]
	s_cbranch_vccnz .Lp1_skipE_l7
	global_load_dword v203, v205, s[98:99] offset:256 nt
.Lp1_skipE_l7:
	ds_read_b128 v[64:67], v141 offset:20480
	ds_read_b128 v[68:71], v141 offset:21504
	s_and_b64 vcc, exec, s[8:9]
	s_waitcnt vmcnt(11) lgkmcnt(1)
	v_mfma_f32_16x16x32_bf16 v[40:43], v[64:67], v[60:63], v[40:43]
	ds_read_b128 v[64:67], v141 offset:22528
	s_waitcnt lgkmcnt(1)
	v_mfma_f32_16x16x32_bf16 v[36:39], v[68:71], v[60:63], v[36:39]
	ds_read_b128 v[68:71], v141 offset:23552
	s_waitcnt lgkmcnt(1)
	v_mfma_f32_16x16x32_bf16 v[32:35], v[64:67], v[60:63], v[32:35]
	s_waitcnt lgkmcnt(0)
	v_mfma_f32_16x16x32_bf16 v[28:31], v[68:71], v[60:63], v[28:31]
	s_cbranch_vccnz .LBB0_152
	ds_read_b128 v[64:67], v141 offset:24576
	s_waitcnt lgkmcnt(0)
	v_mfma_f32_16x16x32_bf16 v[8:11], v[64:67], v[60:63], v[8:11]
.LBB0_152:
	ds_read_b128 v[60:63], v141 offset:25600
	ds_read_b128 v[64:67], v141 offset:26624
	s_and_b64 vcc, exec, s[8:9]
	s_waitcnt vmcnt(10) lgkmcnt(1)
	v_mfma_f32_16x16x32_bf16 v[40:43], v[60:63], v[56:59], v[40:43]
	ds_read_b128 v[60:63], v141 offset:27648
	s_waitcnt lgkmcnt(1)
	v_mfma_f32_16x16x32_bf16 v[36:39], v[64:67], v[56:59], v[36:39]
	ds_read_b128 v[64:67], v141 offset:28672
	s_waitcnt lgkmcnt(1)
	v_mfma_f32_16x16x32_bf16 v[32:35], v[60:63], v[56:59], v[32:35]
	s_waitcnt lgkmcnt(0)
	v_mfma_f32_16x16x32_bf16 v[28:31], v[64:67], v[56:59], v[28:31]
	s_cbranch_vccnz .LBB0_154
	ds_read_b128 v[60:63], v141 offset:29696
	s_waitcnt lgkmcnt(0)
	v_mfma_f32_16x16x32_bf16 v[8:11], v[60:63], v[56:59], v[8:11]
.LBB0_154:
	ds_read_b128 v[56:59], v141 offset:30720
	ds_read_b128 v[60:63], v141 offset:31744
	s_and_b64 vcc, exec, s[8:9]
	s_waitcnt vmcnt(9) lgkmcnt(1)
	v_mfma_f32_16x16x32_bf16 v[40:43], v[56:59], v[52:55], v[40:43]
	ds_read_b128 v[56:59], v141 offset:32768
	s_waitcnt lgkmcnt(1)
	v_mfma_f32_16x16x32_bf16 v[36:39], v[60:63], v[52:55], v[36:39]
	ds_read_b128 v[60:63], v141 offset:33792
	s_waitcnt lgkmcnt(1)
	v_mfma_f32_16x16x32_bf16 v[32:35], v[56:59], v[52:55], v[32:35]
	s_waitcnt lgkmcnt(0)
	v_mfma_f32_16x16x32_bf16 v[28:31], v[60:63], v[52:55], v[28:31]
	s_cbranch_vccnz .LBB0_156
	ds_read_b128 v[56:59], v141 offset:34816
	s_waitcnt lgkmcnt(0)
	v_mfma_f32_16x16x32_bf16 v[8:11], v[56:59], v[52:55], v[8:11]
.LBB0_156:
	ds_read_b128 v[52:55], v141 offset:35840
	ds_read_b128 v[56:59], v141 offset:36864
	s_and_b64 vcc, exec, s[8:9]
	s_waitcnt vmcnt(8) lgkmcnt(1)
	v_mfma_f32_16x16x32_bf16 v[40:43], v[52:55], v[48:51], v[40:43]
	ds_read_b128 v[52:55], v141 offset:37888
	s_waitcnt lgkmcnt(1)
	v_mfma_f32_16x16x32_bf16 v[36:39], v[56:59], v[48:51], v[36:39]
	ds_read_b128 v[56:59], v141 offset:38912
	s_waitcnt lgkmcnt(1)
	v_mfma_f32_16x16x32_bf16 v[32:35], v[52:55], v[48:51], v[32:35]
	s_waitcnt lgkmcnt(0)
	v_mfma_f32_16x16x32_bf16 v[28:31], v[56:59], v[48:51], v[28:31]
	s_cbranch_vccnz .LBB0_158
	ds_read_b128 v[52:55], v141 offset:39936
	s_waitcnt lgkmcnt(0)
	v_mfma_f32_16x16x32_bf16 v[8:11], v[52:55], v[48:51], v[8:11]

.LBB0_162:
	s_waitcnt vmcnt(0)
	v_add_u32_e32 v3, s21, v98
	v_add_u32_e32 v207, 0xa000, v206
	v_cvt_pk_bf16_f32 v44, v164, v168
	v_cvt_pk_bf16_f32 v45, v172, v176
	v_cvt_pk_bf16_f32 v46, v180, v184
	v_cvt_pk_bf16_f32 v47, v188, v192
	ds_write_b128 v207, v[44:47]
	v_cvt_pk_bf16_f32 v44, v165, v169
	v_cvt_pk_bf16_f32 v45, v173, v177
	v_cvt_pk_bf16_f32 v46, v181, v185
	v_cvt_pk_bf16_f32 v47, v189, v193
	ds_write_b128 v207, v[44:47] offset:16
	v_cvt_pk_bf16_f32 v44, v166, v170
	v_cvt_pk_bf16_f32 v45, v174, v178
	v_cvt_pk_bf16_f32 v46, v182, v186
	v_cvt_pk_bf16_f32 v47, v190, v194
	ds_write_b128 v207, v[44:47] offset:32
	v_cvt_pk_bf16_f32 v44, v167, v171
	v_cvt_pk_bf16_f32 v45, v175, v179
	v_cvt_pk_bf16_f32 v46, v183, v187
	v_cvt_pk_bf16_f32 v47, v191, v195
	ds_write_b128 v207, v[44:47] offset:48
	s_and_b64 vcc, exec, s[8:9]
	s_cbranch_vccnz .LBB0_164
	v_cvt_pk_bf16_f32 v44, v196, v197
	v_cvt_pk_bf16_f32 v45, v198, v199
	v_cvt_pk_bf16_f32 v46, v200, v201
	v_cvt_pk_bf16_f32 v47, v202, v203
	ds_write_b128 v3, v[44:47] offset:45056

.LBB0_682:
	s_waitcnt vmcnt(8)
	v_xor_b32_e32 v3, 0x80000000, v3
	v_xor_b32_e32 v2, 0x80000000, v2
	s_and_b32 s8, s31, 0xfffff800
	v_cvt_pk_bf16_f32 v38, v38, v39
	v_cvt_pk_bf16_f32 v39, v40, v41
	v_cvt_pk_bf16_f32 v41, v36, v37
	v_cvt_pk_bf16_f32 v36, v2, v3
	v_add_u32_e32 v2, s8, v143
	s_and_b32 s8, s92, 7
	s_lshl_b32 s9, s33, 5
	v_ashrrev_i32_e32 v3, 31, v2
	s_lshl_b32 s8, s8, 5
	s_and_b32 s9, s9, 0x700
	v_lshlrev_b64 v[2:3], 12, v[2:3]
	s_or_b32 s8, s9, s8
	s_add_i32 s6, s89, s21
	v_xor_b32_e32 v17, 0x80000000, v17
	v_xor_b32_e32 v16, 0x80000000, v16
	v_xor_b32_e32 v15, 0x80000000, v15
	v_xor_b32_e32 v14, 0x80000000, v14
	v_xor_b32_e32 v13, 0x80000000, v13
	v_xor_b32_e32 v12, 0x80000000, v12
	v_xor_b32_e32 v11, 0x80000000, v11
	v_xor_b32_e32 v10, 0x80000000, v10
	s_waitcnt vmcnt(7)
	v_xor_b32_e32 v9, 0x80000000, v9
	v_xor_b32_e32 v8, 0x80000000, v8
	v_xor_b32_e32 v7, 0x80000000, v7
	v_xor_b32_e32 v6, 0x80000000, v6
	v_xor_b32_e32 v5, 0x80000000, v5
	v_xor_b32_e32 v4, 0x80000000, v4
	v_or_b32_e32 v2, s8, v2
	s_lshl_b32 s3, s3, 5
	v_cvt_pk_bf16_f32 v40, v34, v35
	v_cvt_pk_bf16_f32 v30, v30, v31
	v_cvt_pk_bf16_f32 v31, v32, v33
	v_cvt_pk_bf16_f32 v32, v26, v27
	v_cvt_pk_bf16_f32 v33, v28, v29
	v_cvt_pk_bf16_f32 v26, v14, v15
	v_cvt_pk_bf16_f32 v27, v16, v17
	v_cvt_pk_bf16_f32 v28, v10, v11
	v_cvt_pk_bf16_f32 v29, v12, v13
	v_cvt_pk_bf16_f32 v34, v6, v7
	v_cvt_pk_bf16_f32 v35, v8, v9
	v_cvt_pk_bf16_f32 v37, v4, v5
	s_waitcnt vmcnt(5)
	v_cvt_pk_bf16_f32 v46, v1, v191
	s_waitcnt vmcnt(3)
	v_cvt_pk_bf16_f32 v47, v192, v193
	v_lshl_add_u64 v[54:55], v[94:95], 0, v[2:3]
	v_xor_b32_e32 v56, 0x80000000, v108
	v_mov_b32_e32 v57, v108
	s_add_i32 s82, s97, s3
	v_mov_b32_e32 v2, v77
	v_mov_b32_e32 v1, v77
	v_mov_b32_e32 v4, v77
	v_mov_b32_e32 v3, v77
	v_mov_b32_e32 v6, v77
	v_mov_b32_e32 v5, v77
	v_mov_b32_e32 v8, v77
	v_mov_b32_e32 v7, v77
	v_mov_b32_e32 v10, v77
	v_mov_b32_e32 v9, v77
	v_mov_b32_e32 v12, v77
	v_mov_b32_e32 v11, v77
	v_mov_b32_e32 v14, v77
	s_mov_b32 s83, 0x20000
	s_mov_b32 s3, s6
	v_mov_b32_e32 v13, v77
	v_mov_b32_e32 v16, v77
	v_mov_b32_e32 v15, v77
	s_waitcnt vmcnt(0)
.LBB0_683:
	s_and_b32 s6, s83, 0x78000
	s_lshl_b32 s6, s6, 1
	v_lshl_add_u64 v[64:65], v[44:45], 0, s[6:7]
	v_mov_b64_e32 v[62:63], v[112:113]
	v_mov_b64_e32 v[112:113], v[114:115]
	s_waitcnt vmcnt(3)
	v_mov_b64_e32 v[114:115], v[116:117]
	global_load_dwordx2 v[116:117], v[64:65], off
	s_ashr_i32 s6, s3, 1
	s_cmpk_lt_i32 s3, 0x6800
	s_cselect_b64 vcc, -1, 0
	s_and_b64 s[8:9], vcc, exec
	s_cselect_b32 s24, s6, 0
	s_cmpk_gt_i32 s24, 0x2bff
	s_cselect_b64 s[90:91], -1, 0
	s_and_b64 s[8:9], s[90:91], exec
	s_cselect_b32 s25, 0x800, s28
	s_cselect_b32 s23, 0xffffd400, s29
	s_cmpk_lt_i32 s24, 0x1600
	s_cselect_b64 s[92:93], -1, 0
	s_and_b64 s[8:9], s[92:93], exec
	s_cselect_b32 s89, 0, s23
	s_add_i32 s89, s89, s24
	s_cmpk_gt_i32 s3, 0x67ff
	s_cbranch_scc1 .LBB0_685
	s_cmpk_lt_u32 s6, 0x2c00
	s_cselect_b32 s6, s5, 0xe0
	s_and_b64 s[8:9], s[92:93], exec
	s_cselect_b32 s6, 0xf0, s6
	s_add_u32 s8, s0, s6
	s_addc_u32 s9, s1, 0
	s_lshr_b32 s6, s25, 5
	s_abs_i32 s87, s6
	v_cvt_f32_u32_e32 v1, s87
	s_sub_i32 s92, 0, s87
	s_abs_i32 s86, s89
	s_xor_b32 s23, s89, s6
	v_rcp_iflag_f32_e32 v1, v1
	s_ashr_i32 s23, s23, 31
	s_load_dwordx2 s[8:9], s[8:9], 0x0
	v_mul_f32_e32 v1, 0x4f7ffffe, v1
	v_cvt_u32_f32_e32 v1, v1
	s_nop 0
	v_readfirstlane_b32 s93, v1
	s_mul_i32 s92, s92, s93
	s_mul_hi_u32 s92, s93, s92
	s_add_i32 s93, s93, s92
	s_mul_hi_u32 s92, s86, s93
	s_mul_i32 s93, s92, s87
	s_sub_i32 s86, s86, s93
	s_add_i32 s93, s92, 1
	s_sub_i32 s35, s86, s87
	s_cmp_ge_u32 s86, s87
	s_cselect_b32 s92, s93, s92
	s_cselect_b32 s35, s35, s86
	s_add_i32 s86, s92, 1
	s_cmp_ge_u32 s35, s87
	s_cselect_b32 s35, s86, s92
	s_xor_b32 s35, s35, s23
	s_sub_i32 s23, s35, s23
	s_mul_i32 s6, s23, s6
	s_lshl_b32 s23, s23, 6
	s_and_b32 s35, s82, 32
	s_or_b32 s23, s23, s35
	s_sub_i32 s6, s89, s6
	v_or_b32_e32 v1, s23, v99
	s_lshl_b32 s86, s6, 5
	v_mad_i64_i32 v[2:3], s[92:93], v1, s25, 0
	s_waitcnt lgkmcnt(0)
	v_lshl_add_u64 v[2:3], v[2:3], 2, s[8:9]
	s_ashr_i32 s87, s86, 31
	v_lshl_add_u64 v[2:3], s[86:87], 2, v[2:3]
	v_lshl_add_u64 v[64:65], v[2:3], 0, v[76:77]
	s_lshl_b32 s6, s25, 3
	v_lshl_add_u64 v[4:5], v[64:65], 0, s[6:7]
	s_lshl_b32 s6, s25, 4
	global_load_dword v2, v[64:65], off nt
	global_load_dword v1, v[4:5], off nt
	v_lshl_add_u64 v[4:5], v[64:65], 0, s[6:7]
	s_mul_i32 s6, s25, 24
	v_lshl_add_u64 v[6:7], v[64:65], 0, s[6:7]
	s_lshl_b32 s6, s25, 5
	global_load_dword v4, v[4:5], off nt
	s_nop 0
	global_load_dword v3, v[6:7], off nt
	v_lshl_add_u64 v[6:7], v[64:65], 0, s[6:7]
	s_mul_i32 s6, s25, 40
	v_lshl_add_u64 v[8:9], v[64:65], 0, s[6:7]
	s_mul_i32 s6, s25, 48
	global_load_dword v6, v[6:7], off nt
	s_nop 0
	global_load_dword v5, v[8:9], off nt
	v_lshl_add_u64 v[8:9], v[64:65], 0, s[6:7]
	s_mul_i32 s6, s25, 56
	v_lshl_add_u64 v[10:11], v[64:65], 0, s[6:7]
	s_lshl_b32 s6, s25, 6
	global_load_dword v8, v[8:9], off nt
	s_nop 0
	global_load_dword v7, v[10:11], off nt
	v_lshl_add_u64 v[10:11], v[64:65], 0, s[6:7]
	s_mul_i32 s6, s25, 0x48
	v_lshl_add_u64 v[12:13], v[64:65], 0, s[6:7]
	s_mul_i32 s6, s25, 0x50
	global_load_dword v10, v[10:11], off nt
	s_nop 0
	global_load_dword v9, v[12:13], off nt
	v_lshl_add_u64 v[12:13], v[64:65], 0, s[6:7]
	s_mul_i32 s6, s25, 0x58
	v_lshl_add_u64 v[14:15], v[64:65], 0, s[6:7]
	s_mul_i32 s6, s25, 0x60
	global_load_dword v12, v[12:13], off nt
	s_nop 0
	global_load_dword v11, v[14:15], off nt
	v_lshl_add_u64 v[14:15], v[64:65], 0, s[6:7]
	s_mul_i32 s6, s25, 0x68
	v_lshl_add_u64 v[16:17], v[64:65], 0, s[6:7]
	s_mul_i32 s6, s25, 0x70
	global_load_dword v14, v[14:15], off nt
	s_nop 0
	global_load_dword v13, v[16:17], off nt
	v_lshl_add_u64 v[16:17], v[64:65], 0, s[6:7]
	s_mul_i32 s6, s25, 0x78
	v_lshl_add_u64 v[64:65], v[64:65], 0, s[6:7]
	global_load_dword v16, v[16:17], off nt
	s_nop 0
	global_load_dword v15, v[64:65], off nt
.LBB0_685:
	v_lshlrev_b32_e32 v64, 16, v118
	v_and_b32_e32 v65, 0xffff0000, v118
	v_lshlrev_b32_e32 v70, 16, v119
	v_and_b32_e32 v71, 0xffff0000, v119
	v_cvt_pk_bf16_f32 v118, v64, v65
	v_cvt_pk_bf16_f32 v119, v70, v71
	v_add_u32_e32 v17, 0x400, v153
	s_waitcnt lgkmcnt(0)
	s_andn2_b64 vcc, exec, vcc
	v_mfma_f32_16x16x16_bf16 v[126:129], v[118:119], v[124:125], 0
	v_mfma_f32_16x16x16_bf16 v[192:195], v[118:119], v[68:69], 0
	v_mfma_f32_16x16x16_bf16 v[196:199], v[118:119], v[60:61], 0
	v_mfma_f32_16x16x16_bf16 v[200:203], v[118:119], v[52:53], 0
	s_nop 5
	ds_write2_b32 v153, v126, v192 offset1:16
	ds_write2_b32 v153, v127, v193 offset0:132 offset1:148
	ds_write2_b32 v17, v128, v194 offset0:8 offset1:24
	v_mfma_f32_16x16x16_bf16 v[204:207], v[118:119], v[66:67], 0
	ds_write2_b32 v17, v129, v195 offset0:140 offset1:156
	ds_write2_b32 v153, v196, v200 offset0:32 offset1:48
	ds_write2_b32 v153, v197, v201 offset0:164 offset1:180
	v_mfma_f32_16x16x16_bf16 v[126:129], v[118:119], v[58:59], 0
	ds_write2_b32 v17, v198, v202 offset0:40 offset1:56
	ds_write2_b32 v17, v199, v203 offset0:172 offset1:188
	s_nop 5
	ds_write2_b32 v153, v204, v126 offset0:64 offset1:80
	ds_write2_b32 v153, v205, v127 offset0:196 offset1:212
	ds_write2_b32 v17, v206, v128 offset0:72 offset1:88
	ds_write2_b32 v17, v207, v129 offset0:204 offset1:220
	v_mfma_f32_16x16x16_bf16 v[192:195], v[118:119], v[50:51], 0
	v_mfma_f32_16x16x16_bf16 v[126:129], v[118:119], v[42:43], 0
	s_nop 7
	ds_write2_b32 v153, v192, v126 offset0:96 offset1:112
	ds_write2_b32 v153, v193, v127 offset0:228 offset1:244
	ds_write2_b32 v17, v194, v128 offset0:104 offset1:120
	ds_write2_b32 v17, v195, v129 offset0:236 offset1:252
	s_waitcnt lgkmcnt(0)
	ds_read2st64_b32 v[118:119], v75 offset1:1
	ds_read2_b32 v[126:127], v75 offset0:132 offset1:196
	s_waitcnt lgkmcnt(1)
	v_pk_fma_f32 v[118:119], v[110:111], v[48:49], v[118:119]
	v_pk_mov_b32 v[48:49], v[48:49], v[48:49] op_sel:[1,0]
	s_nop 0
	v_pk_fma_f32 v[48:49], v[56:57], v[48:49], v[118:119]
	ds_read2st64_b32 v[118:119], v146 offset0:4 offset1:5
	s_waitcnt lgkmcnt(1)
	v_pk_fma_f32 v[126:127], v[110:111], v[48:49], v[126:127]
	ds_write2st64_b32 v75, v48, v49 offset1:1
	v_pk_fma_f32 v[48:49], v[56:57], v[48:49], v[126:127] op_sel:[0,1,0] op_sel_hi:[1,0,1]
	ds_read2st64_b32 v[126:127], v142 offset0:6 offset1:7
	s_waitcnt lgkmcnt(2)
	v_pk_fma_f32 v[118:119], v[110:111], v[48:49], v[118:119]
	ds_write2_b32 v75, v48, v49 offset0:132 offset1:196
	v_pk_fma_f32 v[48:49], v[56:57], v[48:49], v[118:119] op_sel:[0,1,0] op_sel_hi:[1,0,1]
	ds_read2st64_b32 v[118:119], v190 offset0:8 offset1:9
	s_waitcnt lgkmcnt(2)
	v_pk_fma_f32 v[126:127], v[110:111], v[48:49], v[126:127]
	ds_write2st64_b32 v146, v48, v49 offset0:4 offset1:5
	v_pk_fma_f32 v[48:49], v[56:57], v[48:49], v[126:127] op_sel:[0,1,0] op_sel_hi:[1,0,1]
	ds_read2st64_b32 v[126:127], v144 offset0:10 offset1:11
	s_waitcnt lgkmcnt(2)
	v_pk_fma_f32 v[118:119], v[110:111], v[48:49], v[118:119]
	ds_write2st64_b32 v142, v48, v49 offset0:6 offset1:7
	v_pk_fma_f32 v[48:49], v[56:57], v[48:49], v[118:119] op_sel:[0,1,0] op_sel_hi:[1,0,1]
	ds_read2st64_b32 v[118:119], v140 offset0:12 offset1:13
	s_waitcnt lgkmcnt(2)
	v_pk_fma_f32 v[126:127], v[110:111], v[48:49], v[126:127]
	ds_write2st64_b32 v190, v48, v49 offset0:8 offset1:9
	v_pk_fma_f32 v[48:49], v[56:57], v[48:49], v[126:127] op_sel:[0,1,0] op_sel_hi:[1,0,1]
	ds_read2st64_b32 v[126:127], v136 offset0:14 offset1:15
	s_waitcnt lgkmcnt(2)
	v_pk_fma_f32 v[118:119], v[110:111], v[48:49], v[118:119]
	ds_write2st64_b32 v144, v48, v49 offset0:10 offset1:11
	v_pk_fma_f32 v[48:49], v[56:57], v[48:49], v[118:119] op_sel:[0,1,0] op_sel_hi:[1,0,1]
	ds_read2st64_b32 v[118:119], v138 offset0:16 offset1:17
	s_waitcnt lgkmcnt(2)
	v_pk_fma_f32 v[126:127], v[110:111], v[48:49], v[126:127]
	ds_write2st64_b32 v140, v48, v49 offset0:12 offset1:13
	v_pk_fma_f32 v[48:49], v[56:57], v[48:49], v[126:127] op_sel:[0,1,0] op_sel_hi:[1,0,1]
	ds_read2st64_b32 v[126:127], v134 offset0:18 offset1:19
	s_waitcnt lgkmcnt(2)
	v_pk_fma_f32 v[118:119], v[110:111], v[48:49], v[118:119]
	ds_write2st64_b32 v136, v48, v49 offset0:14 offset1:15
	v_pk_fma_f32 v[48:49], v[56:57], v[48:49], v[118:119] op_sel:[0,1,0] op_sel_hi:[1,0,1]
	ds_read2st64_b32 v[118:119], v132 offset0:20 offset1:21
	s_waitcnt lgkmcnt(2)
	v_pk_fma_f32 v[126:127], v[110:111], v[48:49], v[126:127]
	ds_write2st64_b32 v138, v48, v49 offset0:16 offset1:17
	v_pk_fma_f32 v[48:49], v[56:57], v[48:49], v[126:127] op_sel:[0,1,0] op_sel_hi:[1,0,1]
	ds_read2st64_b32 v[126:127], v131 offset0:22 offset1:23
	s_waitcnt lgkmcnt(2)
	v_pk_fma_f32 v[118:119], v[110:111], v[48:49], v[118:119]
	ds_write2st64_b32 v134, v48, v49 offset0:18 offset1:19
	v_pk_fma_f32 v[48:49], v[56:57], v[48:49], v[118:119] op_sel:[0,1,0] op_sel_hi:[1,0,1]
	ds_read2st64_b32 v[118:119], v130 offset0:24 offset1:25
	s_waitcnt lgkmcnt(2)
	v_pk_fma_f32 v[126:127], v[110:111], v[48:49], v[126:127]
	ds_write2st64_b32 v132, v48, v49 offset0:20 offset1:21
	v_pk_fma_f32 v[48:49], v[56:57], v[48:49], v[126:127] op_sel:[0,1,0] op_sel_hi:[1,0,1]
	ds_read2st64_b32 v[126:127], v107 offset0:26 offset1:27
	s_waitcnt lgkmcnt(2)
	v_pk_fma_f32 v[118:119], v[110:111], v[48:49], v[118:119]
	ds_write2st64_b32 v131, v48, v49 offset0:22 offset1:23
	v_pk_fma_f32 v[48:49], v[56:57], v[48:49], v[118:119] op_sel:[0,1,0] op_sel_hi:[1,0,1]
	ds_read2st64_b32 v[118:119], v73 offset0:28 offset1:29
	s_waitcnt lgkmcnt(2)
	v_pk_fma_f32 v[126:127], v[110:111], v[48:49], v[126:127]
	ds_write2st64_b32 v130, v48, v49 offset0:24 offset1:25
	v_pk_fma_f32 v[48:49], v[56:57], v[48:49], v[126:127] op_sel:[0,1,0] op_sel_hi:[1,0,1]
	ds_read2st64_b32 v[126:127], v72 offset0:30 offset1:31
	s_waitcnt lgkmcnt(2)
	v_pk_fma_f32 v[118:119], v[110:111], v[48:49], v[118:119]
	ds_write2st64_b32 v107, v48, v49 offset0:26 offset1:27
	v_pk_fma_f32 v[48:49], v[56:57], v[48:49], v[118:119] op_sel:[0,1,0] op_sel_hi:[1,0,1]
	ds_write2st64_b32 v73, v48, v49 offset0:28 offset1:29
	s_waitcnt lgkmcnt(2)
	v_pk_fma_f32 v[118:119], v[110:111], v[48:49], v[126:127]
	s_nop 0
	v_pk_fma_f32 v[48:49], v[56:57], v[48:49], v[118:119] op_sel:[0,1,0] op_sel_hi:[1,0,1]
	ds_write2st64_b32 v72, v48, v49 offset0:30 offset1:31
	s_waitcnt lgkmcnt(0)
	ds_read_b128 v[126:129], v154
	ds_read_b128 v[192:195], v154 offset:16
	ds_read_b128 v[196:199], v154 offset:128
	ds_read_b128 v[200:203], v154 offset:144
	ds_read_b128 v[204:207], v154 offset:256
	ds_read_b128 v[208:211], v154 offset:272
	ds_read_b128 v[212:215], v154 offset:384
	ds_read_b128 v[216:219], v154 offset:400
	s_waitcnt lgkmcnt(7)
	v_cvt_pk_bf16_f32 v126, v126, v127
	v_cvt_pk_bf16_f32 v127, v128, v129
	s_waitcnt lgkmcnt(6)
	v_cvt_pk_bf16_f32 v128, v192, v193
	v_cvt_pk_bf16_f32 v129, v194, v195
	s_waitcnt lgkmcnt(5)
	v_cvt_pk_bf16_f32 v192, v196, v197
	v_cvt_pk_bf16_f32 v193, v198, v199
	v_mfma_f32_16x16x32_bf16 v[126:129], v[38:41], v[126:129], 0
	s_waitcnt lgkmcnt(4)
	v_cvt_pk_bf16_f32 v194, v200, v201
	v_cvt_pk_bf16_f32 v195, v202, v203
	s_waitcnt lgkmcnt(0)
	s_nop 1
	v_mfma_f32_16x16x32_bf16 v[126:129], v[30:33], v[192:195], v[126:129]
	s_waitcnt lgkmcnt(3)
	v_cvt_pk_bf16_f32 v192, v204, v205
	v_cvt_pk_bf16_f32 v193, v206, v207
	s_waitcnt lgkmcnt(2)
	v_cvt_pk_bf16_f32 v194, v208, v209
	v_cvt_pk_bf16_f32 v195, v210, v211
	s_nop 1
	v_mfma_f32_16x16x32_bf16 v[126:129], v[26:29], v[192:195], v[126:129]
	s_waitcnt lgkmcnt(1)
	v_cvt_pk_bf16_f32 v192, v212, v213
	v_cvt_pk_bf16_f32 v193, v214, v215
	s_waitcnt lgkmcnt(0)
	v_cvt_pk_bf16_f32 v194, v216, v217
	v_cvt_pk_bf16_f32 v195, v218, v219
	s_nop 1
	v_mfma_f32_16x16x32_bf16 v[126:129], v[34:37], v[192:195], v[126:129]
	s_nop 7
	v_pk_fma_f32 v[70:71], v[24:25], v[70:71], v[128:129]
	v_pk_fma_f32 v[64:65], v[22:23], v[64:65], v[126:127]
	v_pk_mul_f32 v[118:119], v[70:71], v[70:71]
	v_pk_mul_f32 v[126:127], v[64:65], v[64:65]
	v_fmamk_f32 v109, v118, 0xbdd2d3e8, v151
	v_mul_f32_e32 v109, v70, v109
	v_fmamk_f32 v118, v119, 0xbdd2d3e8, v151
	v_exp_f32_e32 v109, v109
	v_mul_f32_e32 v118, v71, v118
	v_exp_f32_e32 v119, v118
	v_add_f32_e32 v109, 1.0, v109
	v_rcp_f32_e32 v118, v109
	v_add_f32_e32 v109, 1.0, v119
	v_fmamk_f32 v119, v126, 0xbdd2d3e8, v151
	v_mul_f32_e32 v119, v64, v119
	v_exp_f32_e32 v123, v119
	v_fmamk_f32 v119, v127, 0xbdd2d3e8, v151
	v_mul_f32_e32 v119, v65, v119
	v_exp_f32_e32 v127, v119
	v_rcp_f32_e32 v119, v109
	v_add_f32_e32 v109, 1.0, v123
	v_rcp_f32_e32 v126, v109
	v_add_f32_e32 v109, 1.0, v127
	v_rcp_f32_e32 v127, v109
	v_pk_mul_f32 v[70:71], v[70:71], v[118:119]
	v_pk_mul_f32 v[64:65], v[64:65], v[126:127]
	v_cvt_pk_bf16_f32 v119, v70, v71
	v_cvt_pk_bf16_f32 v118, v64, v65
	s_nop 1
	v_mfma_f32_16x16x16_bf16 v[126:129], v[46:47], v[118:119], 0
	s_nop 7
	v_add_f32_e32 v109, v18, v126
	v_mul_f32_e32 v109, 0xbfb8aa3b, v109
	v_add_f32_e32 v118, v19, v127
	v_exp_f32_e32 v109, v109
	v_mul_f32_e32 v118, 0xbfb8aa3b, v118
	v_exp_f32_e32 v119, v118
	v_add_f32_e32 v109, 1.0, v109
	v_rcp_f32_e32 v118, v109
	v_add_f32_e32 v109, 1.0, v119
	v_add_f32_e32 v119, v20, v128
	v_mul_f32_e32 v119, 0xbfb8aa3b, v119
	v_exp_f32_e32 v123, v119
	v_add_f32_e32 v119, v21, v129
	v_mul_f32_e32 v119, 0xbfb8aa3b, v119
	v_exp_f32_e32 v127, v119
	v_rcp_f32_e32 v119, v109
	v_add_f32_e32 v109, 1.0, v123
	v_rcp_f32_e32 v126, v109
	v_add_f32_e32 v109, 1.0, v127
	v_rcp_f32_e32 v127, v109
	v_pk_mul_f32 v[64:65], v[118:119], v[64:65]
	v_pk_mul_f32 v[70:71], v[126:127], v[70:71]
	v_cvt_pk_bf16_f32 v64, v64, v65
	v_cvt_pk_bf16_f32 v65, v70, v71
	global_store_dwordx2 v[54:55], v[64:65], off
	s_cbranch_vccnz .Lp7_nocv
	s_and_b64 s[8:9], s[90:91], exec
	s_cselect_b32 s6, s42, 0x4200000
	s_add_u32 s6, s18, s6
	s_addc_u32 s23, s19, 0
	s_lshr_b32 s8, s25, 5
	s_abs_i32 s9, s8
	v_cvt_f32_u32_e32 v64, s9
	s_sub_i32 s87, 0, s9
	s_abs_i32 s35, s89
	s_xor_b32 s86, s89, s8
	v_rcp_iflag_f32_e32 v64, v64
	s_addk_i32 s24, 0xea00
	s_ashr_i32 s86, s86, 31
	s_waitcnt vmcnt(15)
	ds_write2_b32 v152, v2, v1 offset1:66
	s_waitcnt vmcnt(13)
	ds_write2_b32 v152, v4, v3 offset0:132 offset1:198
	s_waitcnt vmcnt(11)
	ds_write2_b32 v121, v6, v5 offset0:8 offset1:74
	s_waitcnt vmcnt(9)
	ds_write2_b32 v121, v8, v7 offset0:140 offset1:206
	s_waitcnt vmcnt(7)
	ds_write2_b32 v188, v10, v9 offset0:16 offset1:82
	s_waitcnt vmcnt(5)
	ds_write2_b32 v188, v12, v11 offset0:148 offset1:214
	s_waitcnt vmcnt(3)
	ds_write2_b32 v189, v14, v13 offset0:24 offset1:90
	s_waitcnt vmcnt(1)
	ds_write2_b32 v189, v16, v15 offset0:156 offset1:222
	v_mul_f32_e32 v64, 0x4f7ffffe, v64
	v_cvt_u32_f32_e32 v64, v64
	s_waitcnt lgkmcnt(0)
	v_mov_b32_e32 v123, v77
	v_readfirstlane_b32 s25, v64
	s_mul_i32 s87, s87, s25
	s_mul_hi_u32 s87, s25, s87
	s_add_i32 s25, s25, s87
	s_mul_hi_u32 s25, s35, s25
	s_mul_i32 s87, s25, s9
	s_sub_i32 s35, s35, s87
	s_add_i32 s92, s25, 1
	s_sub_i32 s87, s35, s9
	s_cmp_ge_u32 s35, s9
	s_cselect_b32 s25, s92, s25
	s_cselect_b32 s35, s87, s35
	s_add_i32 s87, s25, 1
	s_cmp_ge_u32 s35, s9
	s_cselect_b32 s9, s87, s25
	s_xor_b32 s9, s9, s86
	s_sub_i32 s9, s9, s86
	s_mul_i32 s8, s9, s8
	s_sub_i32 s8, s89, s8
	s_lshl_b32 s35, s8, 5
	s_lshl_b32 s8, s8, 6
	s_and_b32 s25, s82, 32
	s_and_b32 s8, s8, 0xffffff00
	s_and_b32 s86, s35, 0x60
	s_cmpk_lt_u32 s24, 0x1600
	s_cselect_b32 s24, 0x80, 0
	s_or_b32 s24, s86, s24
	s_or_b32 s86, s24, s8
	s_lshl_b32 s8, s9, 6
	s_or_b32 s8, s8, s25
	s_and_b64 s[24:25], s[90:91], exec
	s_cselect_b32 s24, s35, s86
	s_ashr_i32 s9, s8, 31
	ds_read2_b32 v[64:65], v103 offset1:16
	ds_read2_b32 v[70:71], v103 offset0:33 offset1:49
	ds_read2_b32 v[118:119], v103 offset0:66 offset1:82
	ds_read2_b32 v[192:193], v103 offset0:99 offset1:115
	ds_read2_b32 v[194:195], v103 offset0:132 offset1:148
	ds_read2_b32 v[196:197], v103 offset0:165 offset1:181
	ds_read2_b32 v[198:199], v103 offset0:198 offset1:214
	ds_read2_b32 v[200:201], v103 offset0:231 offset1:247
	s_lshl_b64 s[8:9], s[8:9], 1
	s_add_u32 s8, s6, s8
	v_or_b32_e32 v202, s24, v101
	s_addc_u32 s9, s23, s9
	v_ashrrev_i32_e32 v203, 31, v202
	v_lshlrev_b64 v[202:203], 12, v[202:203]
	v_lshl_add_u64 v[204:205], s[8:9], 0, v[122:123]
	s_waitcnt lgkmcnt(6)
	v_cvt_pk_bf16_f32 v126, v64, v70
	s_waitcnt lgkmcnt(4)
	v_cvt_pk_bf16_f32 v127, v118, v192
	s_waitcnt lgkmcnt(2)
	v_cvt_pk_bf16_f32 v128, v194, v196
	s_waitcnt lgkmcnt(0)
	v_cvt_pk_bf16_f32 v129, v198, v200
	v_lshl_add_u64 v[202:203], v[204:205], 0, v[202:203]
	v_or_b32_e32 v64, s24, v133
	global_store_dwordx4 v[202:203], v[126:129], off
	s_nop 1
	v_cvt_pk_bf16_f32 v126, v65, v71
	v_ashrrev_i32_e32 v65, 31, v64
	v_lshlrev_b64 v[64:65], 12, v[64:65]
	v_cvt_pk_bf16_f32 v127, v119, v193
	v_cvt_pk_bf16_f32 v128, v195, v197
	v_cvt_pk_bf16_f32 v129, v199, v201
	v_lshl_add_u64 v[64:65], v[204:205], 0, v[64:65]
	global_store_dwordx4 v[64:65], v[126:129], off
	s_waitcnt lgkmcnt(0)
	s_branch .LBB0_687
.Lp7_nocv:
	s_waitcnt vmcnt(1)

	.amdhsa_kernel _Z10fwd_kernelILb1EEv6Params
		.amdhsa_group_segment_fixed_size 0
		.amdhsa_private_segment_fixed_size 0
		.amdhsa_kernarg_size 552
		.amdhsa_user_sgpr_count 2
		.amdhsa_user_sgpr_dispatch_ptr 0
		.amdhsa_user_sgpr_queue_ptr 0
		.amdhsa_user_sgpr_kernarg_segment_ptr 1
		.amdhsa_user_sgpr_dispatch_id 0
		.amdhsa_user_sgpr_kernarg_preload_length 0
		.amdhsa_user_sgpr_kernarg_preload_offset 0
		.amdhsa_user_sgpr_private_segment_size 0
		.amdhsa_uses_dynamic_stack 0
		.amdhsa_enable_private_segment 0
		.amdhsa_system_sgpr_workgroup_id_x 1
		.amdhsa_system_sgpr_workgroup_id_y 0
		.amdhsa_system_sgpr_workgroup_id_z 0
		.amdhsa_system_sgpr_workgroup_info 0
		.amdhsa_system_vgpr_workitem_id 0
		.amdhsa_next_free_vgpr 231
		.amdhsa_next_free_sgpr 102
		.amdhsa_accum_offset 232
		.amdhsa_reserve_vcc 1
		.amdhsa_float_round_mode_32 0
		.amdhsa_float_round_mode_16_64 0
		.amdhsa_float_denorm_mode_32 3
		.amdhsa_float_denorm_mode_16_64 3
		.amdhsa_dx10_clamp 1
		.amdhsa_ieee_mode 1
		.amdhsa_fp16_overflow 0
		.amdhsa_tg_split 0
		.amdhsa_exception_fp_ieee_invalid_op 0
		.amdhsa_exception_fp_denorm_src 0
		.amdhsa_exception_fp_ieee_div_zero 0
		.amdhsa_exception_fp_ieee_overflow 0
		.amdhsa_exception_fp_ieee_underflow 0
		.amdhsa_exception_fp_ieee_inexact 0
		.amdhsa_exception_int_div_zero 0
	.end_amdhsa_kernel

amdhsa.kernels:
  - .agpr_count:     0
    .args:
      - .offset:         0
        .size:           296
        .value_kind:     by_value
      - .offset:         296
        .size:           4
        .value_kind:     hidden_block_count_x
      - .offset:         300
        .size:           4
        .value_kind:     hidden_block_count_y
      - .offset:         304
        .size:           4
        .value_kind:     hidden_block_count_z
      - .offset:         308
        .size:           2
        .value_kind:     hidden_group_size_x
      - .offset:         310
        .size:           2
        .value_kind:     hidden_group_size_y
      - .offset:         312
        .size:           2
        .value_kind:     hidden_group_size_z
      - .offset:         314
        .size:           2
        .value_kind:     hidden_remainder_x
      - .offset:         316
        .size:           2
        .value_kind:     hidden_remainder_y
      - .offset:         318
        .size:           2
        .value_kind:     hidden_remainder_z
      - .offset:         336
        .size:           8
        .value_kind:     hidden_global_offset_x
      - .offset:         344
        .size:           8
        .value_kind:     hidden_global_offset_y
      - .offset:         352
        .size:           8
        .value_kind:     hidden_global_offset_z
      - .offset:         360
        .size:           2
        .value_kind:     hidden_grid_dims
      - .offset:         416
        .size:           4
        .value_kind:     hidden_dynamic_lds_size
    .group_segment_fixed_size: 0
    .kernarg_segment_align: 8
    .kernarg_segment_size: 552
    .language:       OpenCL C
    .language_version:
      - 2
      - 0
    .max_flat_workgroup_size: 512
    .name:           _Z10fwd_kernelILb1EEv6Params
    .private_segment_fixed_size: 0
    .sgpr_count:     108
    .sgpr_spill_count: 55
    .symbol:         _Z10fwd_kernelILb1EEv6Params.kd
    .uniform_work_group_size: 1
    .uses_dynamic_stack: false
    .vgpr_count:     231
    .vgpr_spill_count: 0
    .wavefront_size: 64
  - .agpr_count:     0
    .args:
      - .offset:         0
        .size:           296
        .value_kind:     by_value
      - .offset:         296
        .size:           4
        .value_kind:     hidden_block_count_x
      - .offset:         300
        .size:           4
        .value_kind:     hidden_block_count_y
      - .offset:         304
        .size:           4
        .value_kind:     hidden_block_count_z
      - .offset:         308
        .size:           2
        .value_kind:     hidden_group_size_x
      - .offset:         310
        .size:           2
        .value_kind:     hidden_group_size_y
      - .offset:         312
        .size:           2
        .value_kind:     hidden_group_size_z
      - .offset:         314
        .size:           2
        .value_kind:     hidden_remainder_x
      - .offset:         316
        .size:           2
        .value_kind:     hidden_remainder_y
      - .offset:         318
        .size:           2
        .value_kind:     hidden_remainder_z
      - .offset:         336
        .size:           8
        .value_kind:     hidden_global_offset_x
      - .offset:         344
        .size:           8
        .value_kind:     hidden_global_offset_y
      - .offset:         352
        .size:           8
        .value_kind:     hidden_global_offset_z
      - .offset:         360
        .size:           2
        .value_kind:     hidden_grid_dims
      - .offset:         416
        .size:           4
        .value_kind:     hidden_dynamic_lds_size
    .group_segment_fixed_size: 0
    .kernarg_segment_align: 8
    .kernarg_segment_size: 552
    .language:       OpenCL C
    .language_version:
      - 2
      - 0
    .max_flat_workgroup_size: 512
    .name:           _Z10fwd_kernelILb0EEv6Params
    .private_segment_fixed_size: 0
    .sgpr_count:     104
    .sgpr_spill_count: 48
    .symbol:         _Z10fwd_kernelILb0EEv6Params.kd
    .uniform_work_group_size: 1
    .uses_dynamic_stack: false
    .vgpr_count:     231
    .vgpr_spill_count: 0
    .wavefront_size: 64
